# P6's G output stored cached (nt hint removed): its consumer is the very next phase
# baseline (speedup 1.0000x reference)
.LBB0_575:
	s_lshl_b32 s22, s65, 8
	v_mbcnt_lo_u32_b32 v140, -1, 0
	v_mbcnt_hi_u32_b32 v140, -1, v140
	s_add_i32 s22, s22, s53
	v_and_or_b32 v146, v140, 15, s22
	s_lshl_b32 s22, s66, 8
	v_ashrrev_i32_e32 v140, 1, v140
	v_and_b32_e32 v140, -8, v140
	s_or_b32 s22, s22, s54
	v_add_u32_e32 v140, s22, v140
	v_ashrrev_i32_e32 v141, 31, v140
	v_ashrrev_i32_e32 v147, 31, v146
	v_lshl_add_u64 v[148:149], v[140:141], 1, s[6:7]
	v_lshlrev_b64 v[140:141], 11, v[146:147]
	v_lshl_add_u64 v[140:141], v[148:149], 0, v[140:141]
	v_cvt_pk_bf16_f32 v124, v124, v125
	v_cvt_pk_bf16_f32 v125, v126, v127
	v_cvt_pk_bf16_f32 v126, v120, v121
	v_cvt_pk_bf16_f32 v127, v122, v123
	global_store_dwordx4 v[140:141], v[124:127], off
	v_cvt_pk_bf16_f32 v112, v112, v113
	v_cvt_pk_bf16_f32 v113, v114, v115
	v_cvt_pk_bf16_f32 v114, v104, v105
	v_or_b32_e32 v104, 16, v146
	v_ashrrev_i32_e32 v105, 31, v104
	v_lshlrev_b64 v[104:105], 11, v[104:105]
	v_cvt_pk_bf16_f32 v115, v106, v107
	global_store_dwordx4 v[140:141], v[112:115], off offset:256
	s_nop 1
	v_lshl_add_u64 v[112:113], v[148:149], 0, v[104:105]
	v_cvt_pk_bf16_f32 v104, v116, v117
	v_cvt_pk_bf16_f32 v105, v118, v119
	v_cvt_pk_bf16_f32 v106, v108, v109
	v_cvt_pk_bf16_f32 v107, v110, v111
	global_store_dwordx4 v[112:113], v[104:107], off
	v_cvt_pk_bf16_f32 v96, v96, v97
	v_cvt_pk_bf16_f32 v97, v98, v99
	v_cvt_pk_bf16_f32 v98, v88, v89
	v_or_b32_e32 v88, 32, v146
	v_ashrrev_i32_e32 v89, 31, v88
	v_lshlrev_b64 v[88:89], 11, v[88:89]
	v_cvt_pk_bf16_f32 v99, v90, v91
	global_store_dwordx4 v[112:113], v[96:99], off offset:256
	s_nop 1
	v_lshl_add_u64 v[96:97], v[148:149], 0, v[88:89]
	v_cvt_pk_bf16_f32 v88, v100, v101
	v_cvt_pk_bf16_f32 v89, v102, v103
	v_cvt_pk_bf16_f32 v90, v92, v93
	v_cvt_pk_bf16_f32 v91, v94, v95
	global_store_dwordx4 v[96:97], v[88:91], off
	v_cvt_pk_bf16_f32 v80, v80, v81
	v_cvt_pk_bf16_f32 v81, v82, v83
	v_cvt_pk_bf16_f32 v82, v72, v73
	v_or_b32_e32 v72, 48, v146
	v_ashrrev_i32_e32 v73, 31, v72
	v_lshlrev_b64 v[72:73], 11, v[72:73]
	v_cvt_pk_bf16_f32 v83, v74, v75
	global_store_dwordx4 v[96:97], v[80:83], off offset:256
	s_nop 1
	v_lshl_add_u64 v[80:81], v[148:149], 0, v[72:73]
	v_cvt_pk_bf16_f32 v72, v84, v85
	v_cvt_pk_bf16_f32 v73, v86, v87
	v_cvt_pk_bf16_f32 v74, v76, v77
	v_cvt_pk_bf16_f32 v75, v78, v79
	global_store_dwordx4 v[80:81], v[72:75], off
	v_cvt_pk_bf16_f32 v68, v68, v69
	v_cvt_pk_bf16_f32 v69, v70, v71
	v_cvt_pk_bf16_f32 v70, v64, v65
	v_cvt_pk_bf16_f32 v71, v66, v67
	global_store_dwordx4 v[80:81], v[68:71], off offset:256
	v_cvt_pk_bf16_f32 v60, v60, v61
	v_cvt_pk_bf16_f32 v61, v62, v63
	v_cvt_pk_bf16_f32 v62, v56, v57
	v_add_co_u32_e32 v56, vcc, s59, v140
	v_lshl_add_u64 v[64:65], v[140:141], 0, s[12:13]
	s_nop 0
	v_addc_co_u32_e32 v57, vcc, 0, v141, vcc
	v_cvt_pk_bf16_f32 v63, v58, v59
	global_store_dwordx4 v[56:57], v[60:63], off
	v_cvt_pk_bf16_f32 v48, v48, v49
	v_cvt_pk_bf16_f32 v49, v50, v51
	v_cvt_pk_bf16_f32 v50, v40, v41
	v_cvt_pk_bf16_f32 v51, v42, v43
	global_store_dwordx4 v[64:65], v[48:51], off offset:256
	v_cvt_pk_bf16_f32 v40, v52, v53
	v_cvt_pk_bf16_f32 v41, v54, v55
	v_cvt_pk_bf16_f32 v42, v44, v45
	v_add_co_u32_e32 v44, vcc, s60, v140
	s_nop 0
	v_lshl_add_u64 v[48:49], v[140:141], 0, s[14:15]
	v_addc_co_u32_e32 v45, vcc, 0, v141, vcc
	v_cvt_pk_bf16_f32 v43, v46, v47
	global_store_dwordx4 v[44:45], v[40:43], off
	v_cvt_pk_bf16_f32 v32, v32, v33
	v_cvt_pk_bf16_f32 v33, v34, v35
	v_cvt_pk_bf16_f32 v34, v24, v25
	v_cvt_pk_bf16_f32 v35, v26, v27
	global_store_dwordx4 v[48:49], v[32:35], off offset:256
	v_cvt_pk_bf16_f32 v24, v36, v37
	v_cvt_pk_bf16_f32 v25, v38, v39
	v_cvt_pk_bf16_f32 v26, v28, v29
	v_add_co_u32_e32 v28, vcc, s61, v140
	s_nop 0
	v_lshl_add_u64 v[32:33], v[140:141], 0, s[16:17]
	v_addc_co_u32_e32 v29, vcc, 0, v141, vcc
	v_cvt_pk_bf16_f32 v27, v30, v31
	global_store_dwordx4 v[28:29], v[24:27], off
	v_cvt_pk_bf16_f32 v16, v16, v17
	v_cvt_pk_bf16_f32 v17, v18, v19
	v_cvt_pk_bf16_f32 v18, v8, v9
	v_cvt_pk_bf16_f32 v19, v10, v11
	global_store_dwordx4 v[32:33], v[16:19], off offset:256
	v_cvt_pk_bf16_f32 v8, v20, v21
	v_cvt_pk_bf16_f32 v9, v22, v23
	v_cvt_pk_bf16_f32 v10, v12, v13
	v_add_co_u32_e32 v12, vcc, s62, v140
	s_nop 0
	v_lshl_add_u64 v[16:17], v[140:141], 0, s[18:19]
	v_addc_co_u32_e32 v13, vcc, 0, v141, vcc
	v_cvt_pk_bf16_f32 v11, v14, v15
	global_store_dwordx4 v[12:13], v[8:11], off
	v_cvt_pk_bf16_f32 v4, v4, v5
	v_cvt_pk_bf16_f32 v5, v6, v7
	v_cvt_pk_bf16_f32 v6, v0, v1
	v_cvt_pk_bf16_f32 v7, v2, v3
	global_store_dwordx4 v[16:17], v[4:7], off offset:256
	s_and_b64 vcc, exec, s[2:3]
	s_mov_b64 s[2:3], -1
	s_cbranch_vccnz .LBB0_560
	s_andn2_b64 vcc, exec, s[0:1]
	s_cbranch_vccnz .LBB0_559
	s_barrier
	s_branch .LBB0_559
